# MLA attention loop rewritten: all 8 waves take one software-pipelined path (exp/cvt/row-sum interleaved between MFMAs, persistent -m accumulator init block), plus batched NA bias lookups
# speedup vs baseline: 1.0069x; 1.0000x over previous
.LBB0_530:
	s_or_b64 exec, exec, s[6:7]
	global_load_dwordx4 v[118:121], v[6:7], off offset:128
	v_and_b32_e32 v1, 16, v149
	v_lshlrev_b32_e32 v148, 2, v9
	v_lshlrev_b32_e32 v2, 2, v149
	s_waitcnt lgkmcnt(0)
	s_barrier
	v_and_or_b32 v0, v0, 3, v148
	v_and_or_b32 v1, v2, 12, v1
	v_lshlrev_b32_e32 v155, 6, v153
	v_mul_u32_u24_e32 v0, 0x90, v0
	v_lshlrev_b32_e32 v1, 1, v1
	v_mul_u32_u24_e32 v2, 0xd0, v8
	v_sub_u32_e32 v156, v5, v155
	s_cmpk_lt_u32 s10, 0x100
	v_add3_u32 v149, 0, v4, v2
	v_add3_u32 v97, v1, v0, 0
	v_mul_lo_u32 v151, v152, s81
	v_add_u32_e32 v135, v156, v134
	s_mov_b64 s[6:7], -1
	s_nop 0
	ds_read_b128 v[0:3], v149 offset:6720
	ds_read_b128 v[4:7], v149 offset:6688
	ds_read_b128 v[8:11], v149
	ds_read_b128 v[46:49], v149 offset:32
	ds_read_b128 v[50:53], v149 offset:64
	ds_read_b128 v[54:57], v149 offset:6656
	v_readlane_b32 s40, v254, 47
	s_mov_b32 s12, s40
	v_readlane_b32 s41, v254, 48
	v_readlane_b32 s42, v254, 49
	v_readlane_b32 s43, v254, 50
	v_readlane_b32 s44, v254, 51
	v_readlane_b32 s45, v254, 52
	v_readlane_b32 s46, v254, 53
	v_readlane_b32 s47, v254, 54
	v_readlane_b32 s48, v254, 55
	v_readlane_b32 s49, v254, 56
	v_readlane_b32 s50, v254, 57
	v_readlane_b32 s51, v254, 58
	v_readlane_b32 s52, v254, 59
	v_readlane_b32 s53, v254, 60
	v_readlane_b32 s54, v254, 61
	v_readlane_b32 s55, v254, 62
	v_writelane_b32 v254, s12, 47
	s_mov_b32 s41, s40
	s_mov_b32 s42, s40
	v_writelane_b32 v254, s13, 48
	v_writelane_b32 v254, s14, 49
	v_writelane_b32 v254, s15, 50
	v_writelane_b32 v254, s16, 51
	v_writelane_b32 v254, s17, 52
	s_mov_b32 s43, s40
	s_mov_b32 s44, s40
	s_mov_b32 s45, s40
	s_mov_b32 s46, s40
	s_mov_b32 s47, s40
	s_mov_b32 s48, s40
	s_mov_b32 s49, s40
	s_mov_b32 s50, s40
	s_mov_b32 s51, s40
	s_mov_b32 s52, s40
	s_mov_b32 s53, s40
	s_mov_b32 s54, s40
	s_mov_b32 s55, s40
	v_writelane_b32 v254, s18, 53
	v_mov_b64_e32 v[30:31], s[40:41]
	v_writelane_b32 v254, s19, 54
	v_mov_b64_e32 v[32:33], s[42:43]
	v_mov_b64_e32 v[34:35], s[44:45]
	v_mov_b64_e32 v[36:37], s[46:47]
	v_mov_b64_e32 v[38:39], s[48:49]
	v_mov_b64_e32 v[40:41], s[50:51]
	v_mov_b64_e32 v[42:43], s[52:53]
	v_mov_b64_e32 v[44:45], s[54:55]
	v_writelane_b32 v254, s20, 55
	v_writelane_b32 v254, s21, 56
	s_waitcnt lgkmcnt(3)
	v_mfma_f32_32x32x16_bf16 v[14:29], v[8:11], v[106:109], v[30:45]
	v_writelane_b32 v254, s22, 57
	v_writelane_b32 v254, s23, 58
	v_writelane_b32 v254, s24, 59
	v_writelane_b32 v254, s25, 60
	v_writelane_b32 v254, s26, 61
	v_writelane_b32 v254, s27, 62
	s_waitcnt lgkmcnt(0)
	v_mfma_f32_32x32x16_bf16 v[30:45], v[54:57], v[106:109], v[30:45]
	ds_read_b128 v[8:11], v149 offset:96
	ds_read_b128 v[54:57], v149 offset:6752
	v_mfma_f32_32x32x16_bf16 v[14:29], v[46:49], v[102:105], v[14:29]
	v_mfma_f32_32x32x16_bf16 v[30:45], v[4:7], v[102:105], v[30:45]
	ds_read_b128 v[4:7], v149 offset:128
	ds_read_b128 v[46:49], v149 offset:6784
	v_mfma_f32_32x32x16_bf16 v[14:29], v[50:53], v[92:95], v[14:29]
	v_mfma_f32_32x32x16_bf16 v[30:45], v[0:3], v[92:95], v[30:45]
	ds_read_b128 v[0:3], v149 offset:160
	ds_read_b128 v[50:53], v149 offset:6816
	s_waitcnt lgkmcnt(5)
	v_mfma_f32_32x32x16_bf16 v[14:29], v[8:11], v[88:91], v[14:29]
	s_waitcnt lgkmcnt(4)
	v_mfma_f32_32x32x16_bf16 v[30:45], v[54:57], v[88:91], v[30:45]
	s_waitcnt lgkmcnt(3)
	v_mfma_f32_32x32x16_bf16 v[14:29], v[4:7], v[84:87], v[14:29]
	s_waitcnt lgkmcnt(2)
	v_mfma_f32_32x32x16_bf16 v[30:45], v[46:49], v[84:87], v[30:45]
	s_waitcnt lgkmcnt(1)
	v_mfma_f32_32x32x16_bf16 v[14:29], v[0:3], v[80:83], v[14:29]
	s_waitcnt lgkmcnt(0)
	v_mfma_f32_32x32x16_bf16 v[30:45], v[50:53], v[80:83], v[30:45]
	s_waitcnt vmcnt(1)
	ds_write_b128 v154, v[114:117] offset:13312
	s_and_saveexec_b64 s[6:7], s[38:39]
	v_add3_u32 v0, 0, v151, v136
	ds_write_b128 v0, v[110:113] offset:13440
	s_or_b64 exec, exec, s[6:7]
	s_add_i32 s1, s9, 0x8080
	v_add_u32_e32 v0, s1, v153
	v_ashrrev_i32_e32 v1, 31, v0
	v_lshlrev_b64 v[0:1], 10, v[0:1]
	v_lshl_add_u64 v[0:1], s[92:93], 0, v[0:1]
	v_lshl_add_u64 v[0:1], v[0:1], 0, s[68:69]
	v_lshl_add_u64 v[0:1], v[0:1], 0, v[98:99]
	global_load_dwordx4 v[126:129], v[0:1], off
	v_mov_b64_e32 v[124:125], v[112:113]
	v_mov_b64_e32 v[122:123], v[110:111]
	s_waitcnt vmcnt(1)
	ds_write_b128 v135, v[118:121] offset:26624
	s_and_saveexec_b64 s[6:7], s[38:39]
	s_cbranch_execz .LBB0_535
	v_add_u32_e32 v0, s1, v152
	v_ashrrev_i32_e32 v1, 31, v0
	v_lshlrev_b64 v[0:1], 6, v[0:1]
	v_lshl_add_u64 v[0:1], s[26:27], 0, v[0:1]
	v_lshl_add_u64 v[0:1], v[100:101], 1, v[0:1]
	global_load_dwordx4 v[122:125], v[0:1], off

.LBB0_545:
	s_or_b64 exec, exec, s[6:7]
	v_add_f32_e32 v126, v144, v143
	v_add_f32_e32 v126, 0, v126
	v_add_f32_e32 v64, v145, v64
	v_add_f32_e32 v64, v64, v126
	v_add_f32_e32 v65, v146, v65
	v_add_f32_e32 v64, v65, v64
	v_add_f32_e32 v65, v147, v66
	v_add_f32_e32 v64, v65, v64
	v_add_f32_e32 v65, v157, v67
	v_add_f32_e32 v64, v65, v64
	v_add_f32_e32 v65, v158, v68
	v_add_f32_e32 v64, v65, v64
	v_add_f32_e32 v65, v159, v69
	v_add_f32_e32 v64, v65, v64
	v_add_f32_e32 v65, v160, v70
	v_add_f32_e32 v64, v65, v64
	v_add_f32_e32 v65, v161, v71
	v_add_f32_e32 v64, v65, v64
	v_add_f32_e32 v65, v162, v72
	v_add_f32_e32 v64, v65, v64
	v_add_f32_e32 v65, v163, v73
	v_add_f32_e32 v64, v65, v64
	v_add_f32_e32 v65, v164, v74
	v_add_f32_e32 v64, v65, v64
	v_add_f32_e32 v65, v165, v75
	v_add_f32_e32 v64, v65, v64
	v_add_f32_e32 v65, v166, v76
	v_add_f32_e32 v64, v65, v64
	v_add_f32_e32 v65, v167, v77
	v_add_f32_e32 v64, v65, v64
	v_add_f32_e32 v65, v79, v78
	v_add_f32_e32 v64, v65, v64
	v_add_f32_e32 v138, v138, v64
	v_add_u32_e32 v64, 0x80c0, v142
	v_ashrrev_i32_e32 v65, 31, v64
	v_lshlrev_b64 v[64:65], 10, v[64:65]
	v_lshl_add_u64 v[64:65], s[92:93], 0, v[64:65]
	v_lshl_add_u64 v[64:65], v[64:65], 0, s[68:69]
	v_lshl_add_u64 v[64:65], v[64:65], 0, v[98:99]
	global_load_dwordx4 v[126:129], v[64:65], off offset:128
	s_waitcnt lgkmcnt(0)
	s_barrier
	s_add_u32 s6, s92, s68
	s_addc_u32 s7, s93, 0
	v_lshl_add_u64 v[142:143], s[6:7], 0, v[98:99]
	v_lshl_add_u64 v[144:145], v[100:101], 1, s[26:27]
	v_add3_u32 v146, v152, s8, 64
	s_mov_b32 s1, 4
	v_xor_b32_e32 v64, 0x80000000, v139
	v_mov_b32_e32 v65, v64
	v_mov_b32_e32 v66, v64
	v_mov_b32_e32 v67, v64
	v_mov_b32_e32 v68, v64
	v_mov_b32_e32 v69, v64
	v_mov_b32_e32 v70, v64
	v_mov_b32_e32 v71, v64
	v_mov_b32_e32 v72, v64
	v_mov_b32_e32 v73, v64
	v_mov_b32_e32 v74, v64
	v_mov_b32_e32 v75, v64
	v_mov_b32_e32 v76, v64
	v_mov_b32_e32 v77, v64
	v_mov_b32_e32 v78, v64
	v_mov_b32_e32 v79, v64
.LBB0_546:
	v_max3_f32 v100, v48, v49, v32
	v_max3_f32 v101, v50, v51, v33
	v_max3_f32 v100, v100, v34, v35
	v_max3_f32 v101, v101, v54, v55
	v_max3_f32 v100, v100, v52, v53
	v_max3_f32 v101, v101, v38, v39
	v_max3_f32 v100, v100, v36, v37
	v_max3_f32 v101, v101, v58, v59
	v_max3_f32 v100, v100, v56, v57
	v_max3_f32 v101, v101, v42, v43
	v_max3_f32 v100, v100, v40, v41
	v_max3_f32 v101, v101, v62, v63
	v_max3_f32 v100, v100, v60, v61
	v_max3_f32 v101, v101, v46, v47
	v_max3_f32 v100, v100, v44, v45
	v_max3_f32 v100, v100, v101, v101
	ds_bpermute_b32 v101, v137, v100
	s_waitcnt lgkmcnt(0)
	v_max3_f32 v100, v100, v101, v100
	s_nop 0
	v_cmp_lt_f32_e32 vcc, s78, v100
	s_cbranch_vccz .Lmla_norescale
	v_max_f32_e32 v100, v100, v100
	v_max_f32_e32 v100, 0, v100
	v_exp_f32_e64 v98, -v100
	v_add_f32_e32 v139, v139, v100
	v_pk_add_f32 v[48:49], v[48:49], v[100:101] op_sel_hi:[1,0] neg_lo:[0,1] neg_hi:[0,1]
	v_pk_add_f32 v[32:33], v[32:33], v[100:101] op_sel_hi:[1,0] neg_lo:[0,1] neg_hi:[0,1]
	v_mul_f32_e32 v138, v138, v98
	v_pk_add_f32 v[50:51], v[50:51], v[100:101] op_sel_hi:[1,0] neg_lo:[0,1] neg_hi:[0,1]
	v_pk_add_f32 v[34:35], v[34:35], v[100:101] op_sel_hi:[1,0] neg_lo:[0,1] neg_hi:[0,1]
	v_pk_add_f32 v[52:53], v[52:53], v[100:101] op_sel_hi:[1,0] neg_lo:[0,1] neg_hi:[0,1]
	v_pk_add_f32 v[36:37], v[36:37], v[100:101] op_sel_hi:[1,0] neg_lo:[0,1] neg_hi:[0,1]
	v_pk_add_f32 v[54:55], v[54:55], v[100:101] op_sel_hi:[1,0] neg_lo:[0,1] neg_hi:[0,1]
	v_pk_add_f32 v[38:39], v[38:39], v[100:101] op_sel_hi:[1,0] neg_lo:[0,1] neg_hi:[0,1]
	v_pk_add_f32 v[56:57], v[56:57], v[100:101] op_sel_hi:[1,0] neg_lo:[0,1] neg_hi:[0,1]
	v_pk_add_f32 v[40:41], v[40:41], v[100:101] op_sel_hi:[1,0] neg_lo:[0,1] neg_hi:[0,1]
	v_pk_add_f32 v[58:59], v[58:59], v[100:101] op_sel_hi:[1,0] neg_lo:[0,1] neg_hi:[0,1]
	v_pk_add_f32 v[42:43], v[42:43], v[100:101] op_sel_hi:[1,0] neg_lo:[0,1] neg_hi:[0,1]
	v_pk_add_f32 v[60:61], v[60:61], v[100:101] op_sel_hi:[1,0] neg_lo:[0,1] neg_hi:[0,1]
	v_pk_add_f32 v[44:45], v[44:45], v[100:101] op_sel_hi:[1,0] neg_lo:[0,1] neg_hi:[0,1]
	v_pk_add_f32 v[62:63], v[62:63], v[100:101] op_sel_hi:[1,0] neg_lo:[0,1] neg_hi:[0,1]
	v_pk_add_f32 v[46:47], v[46:47], v[100:101] op_sel_hi:[1,0] neg_lo:[0,1] neg_hi:[0,1]
	v_pk_mul_f32 v[30:31], v[30:31], v[98:99] op_sel_hi:[1,0]
	v_pk_mul_f32 v[28:29], v[28:29], v[98:99] op_sel_hi:[1,0]
	v_pk_mul_f32 v[26:27], v[26:27], v[98:99] op_sel_hi:[1,0]
	v_pk_mul_f32 v[24:25], v[24:25], v[98:99] op_sel_hi:[1,0]
	v_pk_mul_f32 v[22:23], v[22:23], v[98:99] op_sel_hi:[1,0]
	v_pk_mul_f32 v[20:21], v[20:21], v[98:99] op_sel_hi:[1,0]
	v_pk_mul_f32 v[18:19], v[18:19], v[98:99] op_sel_hi:[1,0]
	v_pk_mul_f32 v[16:17], v[16:17], v[98:99] op_sel_hi:[1,0]
	v_pk_mul_f32 v[14:15], v[14:15], v[98:99] op_sel_hi:[1,0]
	v_pk_mul_f32 v[12:13], v[12:13], v[98:99] op_sel_hi:[1,0]
	v_pk_mul_f32 v[10:11], v[10:11], v[98:99] op_sel_hi:[1,0]
	v_pk_mul_f32 v[8:9], v[8:9], v[98:99] op_sel_hi:[1,0]
	v_pk_mul_f32 v[6:7], v[6:7], v[98:99] op_sel_hi:[1,0]
	v_pk_mul_f32 v[4:5], v[4:5], v[98:99] op_sel_hi:[1,0]
	v_pk_mul_f32 v[2:3], v[2:3], v[98:99] op_sel_hi:[1,0]
	v_pk_mul_f32 v[0:1], v[0:1], v[98:99] op_sel_hi:[1,0]
	v_xor_b32_e32 v64, 0x80000000, v139
	v_mov_b32_e32 v65, v64
	v_mov_b32_e32 v66, v64
	v_mov_b32_e32 v67, v64
	v_mov_b32_e32 v68, v64
	v_mov_b32_e32 v69, v64
	v_mov_b32_e32 v70, v64
	v_mov_b32_e32 v71, v64
	v_mov_b32_e32 v72, v64
	v_mov_b32_e32 v73, v64
	v_mov_b32_e32 v74, v64
	v_mov_b32_e32 v75, v64
	v_mov_b32_e32 v76, v64
	v_mov_b32_e32 v77, v64
	v_mov_b32_e32 v78, v64
	v_mov_b32_e32 v79, v64
.Lmla_norescale:
	s_add_i32 s10, s1, -1
	s_and_b32 s11, s10, 1
	s_mul_i32 s7, s11, 0x3400
	v_add_u32_e32 v147, s7, v149
	ds_read_b128 v[110:113], v147
	ds_read_b128 v[114:117], v147 offset:32
	ds_read_b128 v[118:121], v147 offset:64
	ds_read_b128 v[152:155], v147 offset:96
	s_and_b32 s6, s1, 1
	v_exp_f32_e32 v141, v48
	v_exp_f32_e32 v157, v49
	v_exp_f32_e32 v158, v50
	v_exp_f32_e32 v159, v51
	v_exp_f32_e32 v160, v52
	v_exp_f32_e32 v161, v53
	v_exp_f32_e32 v162, v54
	v_exp_f32_e32 v163, v55
	v_exp_f32_e32 v164, v56
	v_exp_f32_e32 v165, v57
	v_exp_f32_e32 v166, v58
	v_exp_f32_e32 v167, v59
	v_exp_f32_e32 v168, v60
	v_exp_f32_e32 v169, v61
	v_exp_f32_e32 v170, v62
	v_exp_f32_e32 v171, v63
	s_waitcnt lgkmcnt(3)
	v_mfma_f32_32x32x16_bf16 v[48:63], v[110:113], v[106:109], v[64:79]
	ds_read_b128 v[234:237], v147 offset:128
	v_exp_f32_e32 v172, v32
	v_exp_f32_e32 v173, v33
	v_exp_f32_e32 v174, v34
	s_waitcnt lgkmcnt(3)
	v_mfma_f32_32x32x16_bf16 v[48:63], v[114:117], v[102:105], v[48:63]
	ds_read_b128 v[212:215], v147 offset:160
	v_exp_f32_e32 v175, v35
	v_exp_f32_e32 v176, v36
	v_exp_f32_e32 v177, v37
	s_waitcnt lgkmcnt(3)
	v_mfma_f32_32x32x16_bf16 v[48:63], v[118:121], v[92:95], v[48:63]
	ds_read_b128 v[216:219], v147 offset:6656
	v_exp_f32_e32 v178, v38
	v_exp_f32_e32 v179, v39
	v_exp_f32_e32 v187, v40
	s_waitcnt lgkmcnt(3)
	v_mfma_f32_32x32x16_bf16 v[48:63], v[152:155], v[88:91], v[48:63]
	ds_read_b128 v[238:241], v147 offset:6688
	v_exp_f32_e32 v188, v41
	v_exp_f32_e32 v189, v42
	v_exp_f32_e32 v190, v43
	s_waitcnt lgkmcnt(3)
	v_mfma_f32_32x32x16_bf16 v[48:63], v[234:237], v[84:87], v[48:63]
	ds_read_b128 v[242:245], v147 offset:6720
	v_exp_f32_e32 v191, v44
	v_exp_f32_e32 v192, v45
	v_exp_f32_e32 v193, v46
	s_waitcnt lgkmcnt(3)
	v_mfma_f32_32x32x16_bf16 v[48:63], v[212:215], v[80:83], v[48:63]
	ds_read_b128 v[246:249], v147 offset:6752
	v_exp_f32_e32 v194, v47
	v_cvt_pk_bf16_f32 v196, v141, v157
	v_cvt_pk_bf16_f32 v197, v158, v159
	s_waitcnt lgkmcnt(3)
	v_mfma_f32_32x32x16_bf16 v[32:47], v[216:219], v[106:109], v[64:79]
	ds_read_b128 v[110:113], v147 offset:6784
	v_cvt_pk_bf16_f32 v198, v160, v161
	v_cvt_pk_bf16_f32 v199, v162, v163
	v_cvt_pk_bf16_f32 v200, v164, v165
	s_waitcnt lgkmcnt(3)
	v_mfma_f32_32x32x16_bf16 v[32:47], v[238:241], v[102:105], v[32:47]
	ds_read_b128 v[114:117], v147 offset:6816
	v_cvt_pk_bf16_f32 v201, v166, v167
	v_cvt_pk_bf16_f32 v202, v168, v169
	v_cvt_pk_bf16_f32 v203, v170, v171
	s_waitcnt lgkmcnt(3)
	v_mfma_f32_32x32x16_bf16 v[32:47], v[242:245], v[92:95], v[32:47]
	s_mul_i32 s7, s6, 0x2400
	v_add_u32_e32 v156, s7, v97
	ds_read_b64_tr_b16 v[118:119], v156 offset:26624
	ds_read_b64_tr_b16 v[120:121], v156 offset:27776
	ds_read_b64_tr_b16 v[154:155], v156 offset:27840
	ds_read_b64_tr_b16 v[152:153], v156 offset:26688
	v_cvt_pk_bf16_f32 v204, v172, v173
	v_cvt_pk_bf16_f32 v205, v174, v175
	s_waitcnt lgkmcnt(6)
	v_mfma_f32_32x32x16_bf16 v[32:47], v[246:249], v[88:91], v[32:47]
	ds_read_b64_tr_b16 v[234:235], v156 offset:28928
	ds_read_b64_tr_b16 v[236:237], v156 offset:30080
	ds_read_b64_tr_b16 v[214:215], v156 offset:30144
	ds_read_b64_tr_b16 v[212:213], v156 offset:28992
	v_cvt_pk_bf16_f32 v206, v176, v177
	v_cvt_pk_bf16_f32 v207, v178, v179
	v_cvt_pk_bf16_f32 v208, v187, v188
	s_waitcnt lgkmcnt(9)
	v_mfma_f32_32x32x16_bf16 v[32:47], v[110:113], v[84:87], v[32:47]
	ds_read_b64_tr_b16 v[216:217], v156 offset:31232
	ds_read_b64_tr_b16 v[218:219], v156 offset:32384
	ds_read_b64_tr_b16 v[240:241], v156 offset:32448
	ds_read_b64_tr_b16 v[238:239], v156 offset:31296
	v_cvt_pk_bf16_f32 v209, v189, v190
	v_cvt_pk_bf16_f32 v210, v191, v192
	v_cvt_pk_bf16_f32 v211, v193, v194
	s_waitcnt lgkmcnt(12)
	v_mfma_f32_32x32x16_bf16 v[32:47], v[114:117], v[80:83], v[32:47]
	ds_read_b64_tr_b16 v[242:243], v156 offset:33536
	ds_read_b64_tr_b16 v[244:245], v156 offset:34688
	ds_read_b64_tr_b16 v[248:249], v156 offset:34752
	ds_read_b64_tr_b16 v[246:247], v156 offset:33600
	v_add_f32_e32 v195, v172, v141
	v_add_f32_e32 v195, 0, v195
	v_add_f32_e32 v101, v173, v157
	v_add_f32_e32 v195, v101, v195
	s_waitcnt lgkmcnt(14)
	v_mfma_f32_32x32x16_bf16 v[16:31], v[118:121], v[196:199], v[16:31]
	v_add_f32_e32 v101, v174, v158
	v_add_f32_e32 v195, v101, v195
	v_add_f32_e32 v101, v175, v159
	v_add_f32_e32 v195, v101, v195
	v_add_f32_e32 v101, v176, v160
	s_waitcnt lgkmcnt(12)
	v_mfma_f32_32x32x16_bf16 v[0:15], v[152:155], v[196:199], v[0:15]
	s_mulk_i32 s6, 0x3400
	s_add_i32 s12, s6, 0
	v_add3_u32 v156, s12, v150, v134
	s_waitcnt vmcnt(1)
	ds_write_b128 v156, v[130:133]
	s_and_saveexec_b64 s[6:7], s[38:39]
	v_add3_u32 v156, s12, v151, v136
	ds_write_b128 v156, v[122:125] offset:128
	s_or_b64 exec, exec, s[6:7]
	v_add_f32_e32 v195, v101, v195
	v_add_f32_e32 v101, v177, v161
	v_add_f32_e32 v195, v101, v195
	s_waitcnt lgkmcnt(11)
	v_mfma_f32_32x32x16_bf16 v[16:31], v[234:237], v[200:203], v[16:31]
	v_add_f32_e32 v101, v178, v162
	v_add_f32_e32 v195, v101, v195
	v_add_f32_e32 v101, v179, v163
	s_waitcnt lgkmcnt(9)
	v_mfma_f32_32x32x16_bf16 v[0:15], v[212:215], v[200:203], v[0:15]
	s_mulk_i32 s11, 0x2400
	v_add_u32_e32 v156, s11, v135
	v_add_u32_e32 v228, 64, v140
	s_waitcnt vmcnt(0)
	ds_write_b128 v156, v[126:129] offset:26624
	s_waitcnt lgkmcnt(8)
	v_mfma_f32_32x32x16_bf16 v[16:31], v[216:219], v[204:207], v[16:31]
	v_add_f32_e32 v195, v101, v195
	v_add_f32_e32 v101, v187, v164
	v_add_f32_e32 v195, v101, v195
	v_add_f32_e32 v101, v188, v165
	v_add_f32_e32 v195, v101, v195
	s_waitcnt lgkmcnt(6)
	v_mfma_f32_32x32x16_bf16 v[0:15], v[238:241], v[204:207], v[0:15]
	s_cmpk_lt_u32 s10, 0x42
	s_cbranch_scc0 .Lmla_noload
	v_ashrrev_i32_e32 v229, 31, v228
	v_lshlrev_b64 v[220:221], 10, v[228:229]
	v_lshl_add_u64 v[220:221], v[142:143], 0, v[220:221]
	global_load_dwordx4 v[130:133], v[220:221], off
	s_and_saveexec_b64 s[6:7], s[38:39]
	s_cbranch_execz .Lmla_norr
	v_ashrrev_i32_e32 v147, 31, v146
	v_lshlrev_b64 v[220:221], 6, v[146:147]
	v_lshl_add_u64 v[220:221], v[144:145], 0, v[220:221]
	global_load_dwordx4 v[122:125], v[220:221], off

.Lmla_noload:
	v_ashrrev_i32_e32 v141, 31, v140
	v_lshlrev_b64 v[220:221], 10, v[140:141]
	v_lshl_add_u64 v[220:221], v[142:143], 0, v[220:221]
	global_load_dwordx4 v[126:129], v[220:221], off offset:128
	s_waitcnt lgkmcnt(4)
	v_mfma_f32_32x32x16_bf16 v[16:31], v[242:245], v[208:211], v[16:31]
	v_add_f32_e32 v101, v189, v166
	v_add_f32_e32 v195, v101, v195
	v_add_f32_e32 v101, v190, v167
	v_add_f32_e32 v195, v101, v195
	v_add_f32_e32 v101, v191, v168
	v_add_f32_e32 v195, v101, v195
	s_waitcnt lgkmcnt(2)
	v_mfma_f32_32x32x16_bf16 v[0:15], v[246:249], v[208:211], v[0:15]
	v_add_f32_e32 v101, v192, v169
	v_add_f32_e32 v195, v101, v195
	v_add_f32_e32 v101, v193, v170
	v_add_f32_e32 v195, v101, v195
	v_add_f32_e32 v101, v194, v171
	v_add_f32_e32 v195, v101, v195
	v_add_f32_e32 v138, v138, v195
	s_waitcnt lgkmcnt(0)
	s_barrier
	s_add_i32 s1, s1, 1
	v_add_u32_e32 v146, 64, v146
	s_cmpk_eq_i32 s1, 0x44
	s_cbranch_scc1 .LBB0_559
	v_mov_b32_e32 v140, v228
	s_branch .LBB0_546
